# speedup vs baseline: 1.0154x; 1.0006x over previous
; template <bool BOUND>
; DEV void attn_tile(const char* kb_, const char* vb_, const float* cl, int kt, bool diag, const int (&qrow)[2], int fr, int fq,
;                    const float (&cq2)[2], const bf16x8 (&qf)[2][2], f32x4 (&o)[2][4], float (&m2)[2], float (&l)[2]) {
;     ...
; #pragma unroll
;   for (int s = 0; s < 4; ++s) {
;     const bf16x8 a0 = *(const bf16x8*)(kb_ + (s * 16 + fr) * 144 + fq * 16);
;     const bf16x8 a1 = *(const bf16x8*)(kb_ + (s * 16 + fr) * 144 + 64 + fq * 16);
; #pragma unroll
;     for (int qs = 0; qs < 2; ++qs) {
;       f32x4 z = f32x4{0.f, 0.f, 0.f, 0.f};
;       z = __builtin_amdgcn_mfma_f32_16x16x32_bf16(a0, qf[qs][0], z, 0, 0, 0);
;       st[qs][s] = __builtin_amdgcn_mfma_f32_16x16x32_bf16(a1, qf[qs][1], z, 0, 0, 0);
;     }
;   }
;   bf16x8 vf[4][2];
; #pragma unroll
;   for (int n = 0; n < 4; ++n)
; #pragma unroll
;     for (int g = 0; g < 2; ++g) {
;       const char* va = vb_ + (n * 16 + fr) * 144 + (g * 32 + fq * 4) * 2;
;       union { bf16x8 v; uint2 u[2]; } av;
;       av.u[0] = *(const uint2*)va;
;       av.u[1] = *(const uint2*)(va + 32);
;       vf[n][g] = av.v;
;     }
;   bf16x8 pf[2][2];
; #pragma unroll
;   for (int qs = 0; qs < 2; ++qs) {
;     if constexpr (BOUND) {
;       float ps = 0.f;
; #pragma unroll
;       for (int s = 0; s < 4; ++s) {
;         const float4 ck = *(const float4*)(cl + kt * 64 + s * 16 + fq * 4);
;         const float ckk[4] = {ck.x, ck.y, ck.z, ck.w};
; #pragma unroll
;         for (int j = 0; j < 4; ++j) {
;           float x = st[qs][s][j] * SC2 + (cq2[qs] - ckk[j]);
;           if (diag) {
;             const int key = kt * 64 + s * 16 + fq * 4 + j;
;             if (key > qrow[qs]) x = -1e30f;
;           }
;           const float pv = __builtin_amdgcn_exp2f(x);
;           st[qs][s][j] = pv;
;           ps += pv;
;         }
;       }
;       l[qs] += ps;
.LBB0_822:
	s_andn2_saveexec_b64 s[26:27], s[26:27]
	s_cbranch_execz .LBB0_824
	s_cbranch_vccz .Lattn_nm0
	v_mfma_f32_16x16x32_bf16 v[230:233], v[132:135], v[12:15], 0
	v_cmp_lt_i32_e64 s[14:15], v222, v176
	ds_read_b128 v[242:245], v140 offset:36992
	v_mfma_f32_16x16x32_bf16 v[230:233], v[128:131], v[16:19], v[230:233]
	v_mfma_f32_16x16x32_bf16 v[234:237], v[132:135], v[28:31], 0
	v_mfma_f32_16x16x32_bf16 v[238:241], v[124:127], v[12:15], 0
	s_nop 5
	v_fmac_f32_e32 v139, 0x3e38aa3b, v231
	v_fmac_f32_e32 v137, 0x3e38aa3b, v230
	v_cndmask_b32_e64 v185, v202, v139, s[14:15]
	v_fmac_f32_e32 v138, 0x3e38aa3b, v232
	v_cmp_gt_i32_e64 s[14:15], v224, v176
	v_fmac_f32_e32 v136, 0x3e38aa3b, v233
	ds_read_b128 v[230:233], v140 offset:36928
	s_and_b64 s[14:15], vcc, s[14:15]
	v_mfma_f32_16x16x32_bf16 v[234:237], v[128:131], v[24:27], v[234:237]
	v_cndmask_b32_e64 v128, v138, v202, s[14:15]
	v_cmp_gt_i32_e64 s[14:15], v223, v176
	s_and_b64 s[14:15], vcc, s[14:15]
	v_mfma_f32_16x16x32_bf16 v[238:241], v[120:123], v[16:19], v[238:241]
	v_exp_f32_e32 v129, v128
	v_cndmask_b32_e64 v128, v136, v202, s[14:15]
	v_exp_f32_e32 v131, v128
	v_mfma_f32_16x16x32_bf16 v[124:127], v[124:127], v[28:31], 0
	s_waitcnt lgkmcnt(0)
	v_sub_f32_e32 v128, v157, v230
	v_cmp_gt_i32_e64 s[14:15], v183, v176
	s_nop 0
	v_fmac_f32_e32 v128, 0x3e38aa3b, v238
	s_and_b64 s[14:15], vcc, s[14:15]
	v_mfma_f32_16x16x32_bf16 v[124:127], v[120:123], v[24:27], v[124:127]
	v_cndmask_b32_e64 v120, v128, v202, s[14:15]
	v_exp_f32_e32 v121, v120
	v_sub_f32_e32 v120, v157, v231
	v_cmp_gt_i32_e64 s[14:15], v221, v176
	v_mfma_f32_16x16x32_bf16 v[246:249], v[116:119], v[12:15], 0
	v_fmac_f32_e32 v120, 0x3e38aa3b, v239
	s_and_b64 s[14:15], vcc, s[14:15]
	v_cndmask_b32_e64 v120, v120, v202, s[14:15]
	v_mfma_f32_16x16x32_bf16 v[116:119], v[116:119], v[28:31], 0
	v_exp_f32_e32 v123, v120
	v_sub_f32_e32 v120, v157, v232
	v_cmp_gt_i32_e64 s[14:15], v220, v176
	v_fmac_f32_e32 v120, 0x3e38aa3b, v240
	s_and_b64 s[14:15], vcc, s[14:15]
	v_mfma_f32_16x16x32_bf16 v[246:249], v[112:115], v[16:19], v[246:249]
	v_cndmask_b32_e64 v137, v137, v202, s[12:13]
	v_cndmask_b32_e32 v139, v139, v185, vcc
	v_exp_f32_e32 v133, v139
	v_mfma_f32_16x16x32_bf16 v[116:119], v[112:115], v[24:27], v[116:119]
	v_cndmask_b32_e64 v112, v120, v202, s[14:15]
	v_exp_f32_e32 v113, v112
	v_sub_f32_e32 v112, v157, v233
	v_cmp_gt_i32_e64 s[14:15], v219, v176
	v_mfma_f32_16x16x32_bf16 v[250:253], v[108:111], v[12:15], 0
	v_fmac_f32_e32 v112, 0x3e38aa3b, v241
	s_and_b64 s[14:15], vcc, s[14:15]
	v_cndmask_b32_e64 v112, v112, v202, s[14:15]
	v_mfma_f32_16x16x32_bf16 v[108:111], v[108:111], v[28:31], 0
	v_exp_f32_e32 v115, v112
	v_sub_f32_e32 v112, v157, v242
	v_cmp_gt_i32_e64 s[14:15], v218, v176
	v_fmac_f32_e32 v112, 0x3e38aa3b, v246
	s_and_b64 s[14:15], vcc, s[14:15]
	v_mfma_f32_16x16x32_bf16 v[238:241], v[104:107], v[16:19], v[250:253]
	v_sub_f32_e32 v114, v177, v231
	v_fmac_f32_e32 v114, 0x3e38aa3b, v125
	v_sub_f32_e32 v120, v177, v232
	v_mfma_f32_16x16x32_bf16 v[250:253], v[104:107], v[24:27], v[108:111]
	v_cndmask_b32_e64 v104, v112, v202, s[14:15]
	v_exp_f32_e32 v105, v104
	v_sub_f32_e32 v104, v157, v243
	v_cmp_gt_i32_e64 s[14:15], v217, v176
	v_fmac_f32_e32 v104, 0x3e38aa3b, v247
	s_and_b64 s[14:15], vcc, s[14:15]
	v_cndmask_b32_e64 v104, v104, v202, s[14:15]
	v_exp_f32_e32 v107, v104
	v_sub_f32_e32 v104, v157, v244
	v_cmp_gt_i32_e64 s[14:15], v216, v176
	v_fmac_f32_e32 v104, 0x3e38aa3b, v248
	s_and_b64 s[14:15], vcc, s[14:15]
	v_cndmask_b32_e64 v104, v104, v202, s[14:15]
	v_exp_f32_e32 v109, v104
	v_sub_f32_e32 v104, v157, v245
	v_fmac_f32_e32 v104, 0x3e38aa3b, v249
	ds_read_b128 v[246:249], v140 offset:37056
	v_cmp_gt_i32_e64 s[14:15], v215, v176
	s_and_b64 s[14:15], vcc, s[14:15]
	v_sub_f32_e32 v112, v177, v230
	v_cndmask_b32_e64 v104, v104, v202, s[14:15]
	v_fmac_f32_e32 v112, 0x3e38aa3b, v124
	v_exp_f32_e32 v111, v104
	s_waitcnt lgkmcnt(0)
; template <bool BOUND>
; DEV void attn_tile(const char* kb_, const char* vb_, const float* cl, int kt, bool diag, const int (&qrow)[2], int fr, int fq,
;                    const float (&cq2)[2], const bf16x8 (&qf)[2][2], f32x4 (&o)[2][4], float (&m2)[2], float (&l)[2]) {
;     ...
;         for (int j = 0; j < 4; ++j) {
;           float x = st[qs][s][j] * SC2 + (cq2[qs] - ckk[j]);
;           if (diag) {
;             const int key = kt * 64 + s * 16 + fq * 4 + j;
;             if (key > qrow[qs]) x = -1e30f;
;           }
;           const float pv = __builtin_amdgcn_exp2f(x);
;           st[qs][s][j] = pv;
;           ps += pv;
;         }
;       }
;       l[qs] += ps;
;     } else {
;     float tmax = -1e30f;
; #pragma unroll
;     for (int s = 0; s < 4; ++s) {
;       const float4 ck = *(const float4*)(cl + kt * 64 + s * 16 + fq * 4);
;       const float ckk[4] = {ck.x, ck.y, ck.z, ck.w};
; #pragma unroll
;       for (int j = 0; j < 4; ++j) {
;         float x = st[qs][s][j] * SC2 + (cq2[qs] - ckk[j]);
;         if (diag) {
;           const int key = kt * 64 + s * 16 + fq * 4 + j;
;           if (key > qrow[qs]) x = -1e30f;
;         }
;         st[qs][s][j] = x;
;         tmax = fmaxf(tmax, x);
;       }
;     }
;     tmax = fmaxf(tmax, __shfl_xor(tmax, 16));
;     tmax = fmaxf(tmax, __shfl_xor(tmax, 32));
;     const float mn = fmaxf(m2[qs], tmax);
;     const float alpha = __builtin_amdgcn_exp2f(m2[qs] - mn);
;     m2[qs] = mn;
;     float ps = 0.f;
; #pragma unroll
;     for (int s = 0; s < 4; ++s)
; #pragma unroll
;       for (int j = 0; j < 4; ++j) {
;         const float pv = __builtin_amdgcn_exp2f(st[qs][s][j] - mn);
;         st[qs][s][j] = pv;
;         ps += pv;
;       }
;     l[qs] = l[qs] * alpha + ps;
; #pragma unroll
;     for (int n = 0; n < 4; ++n) { o[qs][n][0] *= alpha; o[qs][n][1] *= alpha; o[qs][n][2] *= alpha; o[qs][n][3] *= alpha; }
;     }
; #pragma unroll
;     for (int g = 0; g < 2; ++g) {
;       union { bf16x8 v; unsigned u[4]; } pk;
;       pk.u[0] = pack2bf(st[qs][2 * g][0], st[qs][2 * g][1]);
;       pk.u[1] = pack2bf(st[qs][2 * g][2], st[qs][2 * g][3]);
;       pk.u[2] = pack2bf(st[qs][2 * g + 1][0], st[qs][2 * g + 1][1]);
;       pk.u[3] = pack2bf(st[qs][2 * g + 1][2], st[qs][2 * g + 1][3]);
;       pf[qs][g] = pk.v;
;     }
; #pragma unroll
;     for (int n = 0; n < 4; ++n)
; #pragma unroll
	v_sub_f32_e32 v104, v157, v246
	v_cmp_gt_i32_e64 s[14:15], v214, v176
	v_cndmask_b32_e64 v112, v112, v202, s[12:13]
	v_cmp_gt_i32_e64 s[12:13], v221, v143
	v_fmac_f32_e32 v104, 0x3e38aa3b, v238
	s_and_b64 s[14:15], vcc, s[14:15]
	s_and_b64 s[12:13], vcc, s[12:13]
	v_cndmask_b32_e64 v104, v104, v202, s[14:15]
	v_cndmask_b32_e64 v114, v114, v202, s[12:13]
	v_cmp_gt_i32_e64 s[12:13], v220, v143
	v_exp_f32_e32 v135, v104
	v_sub_f32_e32 v104, v157, v247
	v_cmp_gt_i32_e64 s[14:15], v186, v176
	v_fmac_f32_e32 v120, 0x3e38aa3b, v126
	s_and_b64 s[12:13], vcc, s[12:13]
	v_fmac_f32_e32 v104, 0x3e38aa3b, v239
	s_and_b64 s[14:15], vcc, s[14:15]
	v_cndmask_b32_e64 v124, v120, v202, s[12:13]
	v_sub_f32_e32 v120, v177, v233
	v_cmp_gt_i32_e64 s[12:13], v219, v143
	v_cndmask_b32_e64 v104, v104, v202, s[14:15]
	v_fmac_f32_e32 v120, 0x3e38aa3b, v127
	s_and_b64 s[12:13], vcc, s[12:13]
	v_exp_f32_e32 v139, v104
	v_sub_f32_e32 v104, v157, v248
	v_cmp_gt_i32_e64 s[14:15], v184, v176
	v_cndmask_b32_e64 v125, v120, v202, s[12:13]
	v_sub_f32_e32 v120, v177, v242
	v_cmp_gt_i32_e64 s[12:13], v218, v143
	v_fmac_f32_e32 v104, 0x3e38aa3b, v240
	s_and_b64 s[14:15], vcc, s[14:15]
	v_fmac_f32_e32 v120, 0x3e38aa3b, v116
	s_and_b64 s[12:13], vcc, s[12:13]
	v_cndmask_b32_e64 v104, v104, v202, s[14:15]
	v_cndmask_b32_e64 v116, v120, v202, s[12:13]
	v_sub_f32_e32 v120, v177, v243
	v_cmp_gt_i32_e64 s[12:13], v217, v143
	v_exp_f32_e32 v183, v104
	v_sub_f32_e32 v104, v157, v249
	v_cmp_gt_i32_e64 s[14:15], v182, v176
	v_fmac_f32_e32 v120, 0x3e38aa3b, v117
	s_and_b64 s[12:13], vcc, s[12:13]
	v_fmac_f32_e32 v104, 0x3e38aa3b, v241
	s_and_b64 s[14:15], vcc, s[14:15]
	v_cndmask_b32_e64 v117, v120, v202, s[12:13]
	v_sub_f32_e32 v120, v177, v244
	v_cmp_gt_i32_e64 s[12:13], v216, v143
	v_cndmask_b32_e64 v104, v104, v202, s[14:15]
	v_cmp_gt_i32_e64 s[14:15], v222, v143
	v_fmac_f32_e32 v120, 0x3e38aa3b, v118
	s_and_b64 s[12:13], vcc, s[12:13]
	v_fmac_f32_e32 v228, 0x3e38aa3b, v234
	s_and_b64 s[14:15], vcc, s[14:15]
	v_cndmask_b32_e64 v118, v120, v202, s[12:13]
	v_sub_f32_e32 v120, v177, v245
	v_cmp_gt_i32_e64 s[12:13], v215, v143
	v_exp_f32_e32 v185, v104
	v_cndmask_b32_e64 v104, v228, v202, s[14:15]
	v_fmac_f32_e32 v227, 0x3e38aa3b, v235
	v_cmp_lt_i32_e64 s[14:15], v222, v143
	v_fmac_f32_e32 v120, 0x3e38aa3b, v119
	s_and_b64 s[12:13], vcc, s[12:13]
	v_cndmask_b32_e64 v106, v202, v227, s[14:15]
	v_cmp_gt_i32_e64 s[14:15], v224, v143
	v_cndmask_b32_e64 v119, v120, v202, s[12:13]
	v_sub_f32_e32 v120, v177, v246
	v_cmp_gt_i32_e64 s[12:13], v214, v143
	v_fmac_f32_e32 v226, 0x3e38aa3b, v236
	s_and_b64 s[14:15], vcc, s[14:15]
	v_fmac_f32_e32 v120, 0x3e38aa3b, v250
	s_and_b64 s[12:13], vcc, s[12:13]
	v_cndmask_b32_e64 v108, v226, v202, s[14:15]
	v_cmp_gt_i32_e64 s[14:15], v223, v143
	v_cndmask_b32_e64 v120, v120, v202, s[12:13]
	v_sub_f32_e32 v122, v177, v247
	v_cmp_gt_i32_e64 s[12:13], v186, v143
	v_fmac_f32_e32 v225, 0x3e38aa3b, v237
	s_and_b64 s[14:15], vcc, s[14:15]
	v_fmac_f32_e32 v122, 0x3e38aa3b, v251
	s_and_b64 s[12:13], vcc, s[12:13]
	v_cndmask_b32_e32 v106, v227, v106, vcc
	v_cndmask_b32_e64 v110, v225, v202, s[14:15]
	v_cndmask_b32_e64 v122, v122, v202, s[12:13]
	v_sub_f32_e32 v126, v177, v248
	v_cmp_gt_i32_e64 s[12:13], v184, v143
	v_exp_f32_e32 v137, v137
	v_fmac_f32_e32 v126, 0x3e38aa3b, v252
	s_and_b64 s[12:13], vcc, s[12:13]
	v_exp_f32_e32 v134, v120
	v_exp_f32_e32 v138, v122
	v_exp_f32_e32 v136, v104
	v_exp_f32_e32 v132, v106
	v_exp_f32_e32 v128, v108
	v_exp_f32_e32 v130, v110
	v_exp_f32_e32 v120, v112
	v_exp_f32_e32 v122, v114
	v_exp_f32_e32 v112, v124
	v_exp_f32_e32 v114, v125
	v_cndmask_b32_e64 v126, v126, v202, s[12:13]
	v_sub_f32_e32 v127, v177, v249
	v_cmp_gt_i32_e64 s[12:13], v182, v143
	v_fmac_f32_e32 v127, 0x3e38aa3b, v253
	s_and_b64 vcc, vcc, s[12:13]
	v_cndmask_b32_e32 v127, v127, v202, vcc
	v_cvt_pk_bf16_f32 v238, v137, v133
	v_cvt_pk_bf16_f32 v239, v129, v131
	v_cvt_pk_bf16_f32 v240, v121, v123
	v_cvt_pk_bf16_f32 v241, v113, v115
	v_exp_f32_e32 v182, v126
	v_exp_f32_e32 v104, v116
	v_exp_f32_e32 v106, v117
	v_exp_f32_e32 v108, v118
	v_exp_f32_e32 v110, v119
	v_exp_f32_e32 v184, v127
	v_cvt_pk_bf16_f32 v116, v136, v132
	v_cvt_pk_bf16_f32 v117, v128, v130
	v_cvt_pk_bf16_f32 v118, v120, v122
	v_cvt_pk_bf16_f32 v119, v112, v114
	v_mfma_f32_16x16x32_bf16 v[68:71], v[92:95], v[238:241], v[68:71]
	v_cvt_pk_bf16_f32 v188, v105, v107
	v_cvt_pk_bf16_f32 v189, v109, v111
	v_cvt_pk_bf16_f32 v190, v135, v139
	v_mfma_f32_16x16x32_bf16 v[64:67], v[92:95], v[116:119], v[64:67]
	v_cvt_pk_bf16_f32 v191, v183, v185
	v_cvt_pk_bf16_f32 v124, v104, v106
	v_cvt_pk_bf16_f32 v125, v108, v110
	v_cvt_pk_bf16_f32 v126, v134, v138
	v_cvt_pk_bf16_f32 v127, v182, v184
	v_mfma_f32_16x16x32_bf16 v[68:71], v[88:91], v[188:191], v[68:71]
	s_nop 0
	v_mfma_f32_16x16x32_bf16 v[64:67], v[88:91], v[124:127], v[64:67]
	v_add_f32_e64 v88, v136, 0
	v_add_f32_e64 v89, v137, 0
	v_pk_add_f32 v[88:89], v[88:89], v[132:133]
	v_mfma_f32_16x16x32_bf16 v[40:43], v[84:87], v[238:241], v[40:43]
	v_mfma_f32_16x16x32_bf16 v[8:11], v[84:87], v[116:119], v[8:11]
	v_add_f32_e64 v84, v128, v88
	v_add_f32_e64 v85, v129, v89
	v_pk_add_f32 v[84:85], v[130:131], v[84:85]
	v_mfma_f32_16x16x32_bf16 v[40:43], v[80:83], v[188:191], v[40:43]
	v_add_f32_e64 v84, v84, v120
	v_add_f32_e64 v85, v85, v121
	v_mfma_f32_16x16x32_bf16 v[8:11], v[80:83], v[124:127], v[8:11]
	v_add_f32_e64 v80, v122, v84
	v_add_f32_e64 v81, v123, v85
	v_pk_add_f32 v[80:81], v[112:113], v[80:81]
	v_mfma_f32_16x16x32_bf16 v[60:63], v[76:79], v[238:241], v[60:63]
	v_add_f32_e64 v80, v114, v80
	v_add_f32_e64 v81, v115, v81
	v_mfma_f32_16x16x32_bf16 v[4:7], v[76:79], v[116:119], v[4:7]
	v_add_f32_e64 v76, v104, v80
	v_add_f32_e64 v77, v105, v81
	v_pk_add_f32 v[76:77], v[106:107], v[76:77]
	v_mfma_f32_16x16x32_bf16 v[20:23], v[100:103], v[238:241], v[20:23]
	v_add_f32_e64 v76, v108, v76
	v_add_f32_e64 v77, v109, v77
	v_mfma_f32_16x16x32_bf16 v[0:3], v[100:103], v[116:119], v[0:3]
	v_mfma_f32_16x16x32_bf16 v[60:63], v[72:75], v[188:191], v[60:63]
	v_mfma_f32_16x16x32_bf16 v[4:7], v[72:75], v[124:127], v[4:7]
	v_add_f32_e64 v72, v110, v76
	v_add_f32_e64 v73, v111, v77
	v_pk_add_f32 v[72:73], v[134:135], v[72:73]
	v_mfma_f32_16x16x32_bf16 v[20:23], v[96:99], v[188:191], v[20:23]
	v_add_f32_e64 v72, v138, v72
	v_add_f32_e64 v73, v139, v73
	v_pk_add_f32 v[72:73], v[182:183], v[72:73]
	v_mfma_f32_16x16x32_bf16 v[0:3], v[96:99], v[124:127], v[0:3]
	v_add_f32_e64 v72, v184, v72
	v_add_f32_e64 v73, v185, v73
	v_pk_add_f32 v[178:179], v[178:179], v[72:73]

; template <bool BOUND>
; DEV void attn_tile(const char* kb_, const char* vb_, const float* cl, int kt, bool diag, const int (&qrow)[2], int fr, int fq,
;                    const float (&cq2)[2], const bf16x8 (&qf)[2][2], f32x4 (&o)[2][4], float (&m2)[2], float (&l)[2]) {
;     ...
; #pragma unroll
;   for (int s = 0; s < 4; ++s) {
;     const bf16x8 a0 = *(const bf16x8*)(kb_ + (s * 16 + fr) * 144 + fq * 16);
;     const bf16x8 a1 = *(const bf16x8*)(kb_ + (s * 16 + fr) * 144 + 64 + fq * 16);
; #pragma unroll
;     for (int qs = 0; qs < 2; ++qs) {
;       f32x4 z = f32x4{0.f, 0.f, 0.f, 0.f};
;       z = __builtin_amdgcn_mfma_f32_16x16x32_bf16(a0, qf[qs][0], z, 0, 0, 0);
;       st[qs][s] = __builtin_amdgcn_mfma_f32_16x16x32_bf16(a1, qf[qs][1], z, 0, 0, 0);
;     }
;   }
;   bf16x8 vf[4][2];
; #pragma unroll
;   for (int n = 0; n < 4; ++n)
; #pragma unroll
;     for (int g = 0; g < 2; ++g) {
;       const char* va = vb_ + (n * 16 + fr) * 144 + (g * 32 + fq * 4) * 2;
;       union { bf16x8 v; uint2 u[2]; } av;
;       av.u[0] = *(const uint2*)va;
;       av.u[1] = *(const uint2*)(va + 32);
;       vf[n][g] = av.v;
;     }
;   bf16x8 pf[2][2];
; #pragma unroll
;   for (int qs = 0; qs < 2; ++qs) {
;     if constexpr (BOUND) {
;       float ps = 0.f;
; #pragma unroll
;       for (int s = 0; s < 4; ++s) {
;         const float4 ck = *(const float4*)(cl + kt * 64 + s * 16 + fq * 4);
;         const float ckk[4] = {ck.x, ck.y, ck.z, ck.w};
; #pragma unroll
;         for (int j = 0; j < 4; ++j) {
;           float x = st[qs][s][j] * SC2 + (cq2[qs] - ckk[j]);
;           if (diag) {
;             const int key = kt * 64 + s * 16 + fq * 4 + j;
;             if (key > qrow[qs]) x = -1e30f;
;           }
;           const float pv = __builtin_amdgcn_exp2f(x);
;           st[qs][s][j] = pv;
;           ps += pv;
;         }
;       }
;       l[qs] += ps;
.LBB0_844:
	s_andn2_saveexec_b64 s[26:27], s[26:27]
	s_cbranch_execz .LBB0_846
	s_cbranch_vccz .Lattn_nm1
	v_mfma_f32_16x16x32_bf16 v[188:191], v[132:135], v[12:15], 0
	v_cmp_lt_i32_e64 s[14:15], v222, v176
	ds_read_b128 v[238:241], v140 offset:36992
	v_mfma_f32_16x16x32_bf16 v[188:191], v[128:131], v[16:19], v[188:191]
	v_mfma_f32_16x16x32_bf16 v[230:233], v[132:135], v[28:31], 0
	v_mfma_f32_16x16x32_bf16 v[234:237], v[124:127], v[12:15], 0
	s_nop 5
	v_fmac_f32_e32 v139, 0x3e38aa3b, v189
	v_fmac_f32_e32 v137, 0x3e38aa3b, v188
	v_cndmask_b32_e64 v185, v202, v139, s[14:15]
	v_fmac_f32_e32 v138, 0x3e38aa3b, v190
	v_cmp_gt_i32_e64 s[14:15], v224, v176
	v_fmac_f32_e32 v136, 0x3e38aa3b, v191
	ds_read_b128 v[188:191], v140 offset:36928
	s_and_b64 s[14:15], vcc, s[14:15]
	v_mfma_f32_16x16x32_bf16 v[230:233], v[128:131], v[24:27], v[230:233]
	v_cndmask_b32_e64 v128, v138, v202, s[14:15]
	v_cmp_gt_i32_e64 s[14:15], v223, v176
	s_and_b64 s[14:15], vcc, s[14:15]
	v_mfma_f32_16x16x32_bf16 v[234:237], v[120:123], v[16:19], v[234:237]
	v_exp_f32_e32 v129, v128
	v_cndmask_b32_e64 v128, v136, v202, s[14:15]
	v_exp_f32_e32 v131, v128
	v_mfma_f32_16x16x32_bf16 v[124:127], v[124:127], v[28:31], 0
	s_waitcnt lgkmcnt(0)
	v_sub_f32_e32 v128, v157, v188
	v_cmp_gt_i32_e64 s[14:15], v183, v176
	s_nop 0
	v_fmac_f32_e32 v128, 0x3e38aa3b, v234
	s_and_b64 s[14:15], vcc, s[14:15]
	v_mfma_f32_16x16x32_bf16 v[124:127], v[120:123], v[24:27], v[124:127]
	v_cndmask_b32_e64 v120, v128, v202, s[14:15]
	v_exp_f32_e32 v121, v120
	v_sub_f32_e32 v120, v157, v189
	v_cmp_gt_i32_e64 s[14:15], v221, v176
	v_mfma_f32_16x16x32_bf16 v[242:245], v[116:119], v[12:15], 0
	v_fmac_f32_e32 v120, 0x3e38aa3b, v235
	s_and_b64 s[14:15], vcc, s[14:15]
	v_cndmask_b32_e64 v120, v120, v202, s[14:15]
	v_mfma_f32_16x16x32_bf16 v[116:119], v[116:119], v[28:31], 0
	v_exp_f32_e32 v123, v120
	v_sub_f32_e32 v120, v157, v190
	v_cmp_gt_i32_e64 s[14:15], v220, v176
	v_fmac_f32_e32 v120, 0x3e38aa3b, v236
	s_and_b64 s[14:15], vcc, s[14:15]
	v_mfma_f32_16x16x32_bf16 v[242:245], v[112:115], v[16:19], v[242:245]
	v_cndmask_b32_e64 v137, v137, v202, s[12:13]
	v_cndmask_b32_e32 v139, v139, v185, vcc
	v_exp_f32_e32 v133, v139
	v_mfma_f32_16x16x32_bf16 v[116:119], v[112:115], v[24:27], v[116:119]
	v_cndmask_b32_e64 v112, v120, v202, s[14:15]
	v_exp_f32_e32 v113, v112
	v_sub_f32_e32 v112, v157, v191
	v_cmp_gt_i32_e64 s[14:15], v219, v176
	v_mfma_f32_16x16x32_bf16 v[246:249], v[108:111], v[12:15], 0
	v_fmac_f32_e32 v112, 0x3e38aa3b, v237
	s_and_b64 s[14:15], vcc, s[14:15]
	v_cndmask_b32_e64 v112, v112, v202, s[14:15]
	v_mfma_f32_16x16x32_bf16 v[108:111], v[108:111], v[28:31], 0
	v_exp_f32_e32 v115, v112
	v_sub_f32_e32 v112, v157, v238
	v_cmp_gt_i32_e64 s[14:15], v218, v176
	v_fmac_f32_e32 v112, 0x3e38aa3b, v242
	s_and_b64 s[14:15], vcc, s[14:15]
	v_mfma_f32_16x16x32_bf16 v[234:237], v[104:107], v[16:19], v[246:249]
	v_sub_f32_e32 v114, v177, v189
	v_fmac_f32_e32 v114, 0x3e38aa3b, v125
	v_sub_f32_e32 v120, v177, v190
	v_mfma_f32_16x16x32_bf16 v[246:249], v[104:107], v[24:27], v[108:111]
	v_cndmask_b32_e64 v104, v112, v202, s[14:15]
	v_exp_f32_e32 v105, v104
	v_sub_f32_e32 v104, v157, v239
	v_cmp_gt_i32_e64 s[14:15], v217, v176
	v_fmac_f32_e32 v104, 0x3e38aa3b, v243
	s_and_b64 s[14:15], vcc, s[14:15]
	v_cndmask_b32_e64 v104, v104, v202, s[14:15]
	v_exp_f32_e32 v107, v104
	v_sub_f32_e32 v104, v157, v240
	v_cmp_gt_i32_e64 s[14:15], v216, v176
	v_fmac_f32_e32 v104, 0x3e38aa3b, v244
	s_and_b64 s[14:15], vcc, s[14:15]
	v_cndmask_b32_e64 v104, v104, v202, s[14:15]
	v_exp_f32_e32 v109, v104
	v_sub_f32_e32 v104, v157, v241
	v_fmac_f32_e32 v104, 0x3e38aa3b, v245
	ds_read_b128 v[242:245], v140 offset:37056
	v_cmp_gt_i32_e64 s[14:15], v215, v176
	s_and_b64 s[14:15], vcc, s[14:15]
	v_sub_f32_e32 v112, v177, v188
	v_cndmask_b32_e64 v104, v104, v202, s[14:15]
	v_fmac_f32_e32 v112, 0x3e38aa3b, v124
	v_exp_f32_e32 v111, v104
	s_waitcnt lgkmcnt(0)
; template <bool BOUND>
; DEV void attn_tile(const char* kb_, const char* vb_, const float* cl, int kt, bool diag, const int (&qrow)[2], int fr, int fq,
;                    const float (&cq2)[2], const bf16x8 (&qf)[2][2], f32x4 (&o)[2][4], float (&m2)[2], float (&l)[2]) {
;     ...
;         for (int j = 0; j < 4; ++j) {
;           float x = st[qs][s][j] * SC2 + (cq2[qs] - ckk[j]);
;           if (diag) {
;             const int key = kt * 64 + s * 16 + fq * 4 + j;
;             if (key > qrow[qs]) x = -1e30f;
;           }
;           const float pv = __builtin_amdgcn_exp2f(x);
;           st[qs][s][j] = pv;
;           ps += pv;
;         }
;       }
;       l[qs] += ps;
;     } else {
;     float tmax = -1e30f;
; #pragma unroll
;     for (int s = 0; s < 4; ++s) {
;       const float4 ck = *(const float4*)(cl + kt * 64 + s * 16 + fq * 4);
;       const float ckk[4] = {ck.x, ck.y, ck.z, ck.w};
; #pragma unroll
;       for (int j = 0; j < 4; ++j) {
;         float x = st[qs][s][j] * SC2 + (cq2[qs] - ckk[j]);
;         if (diag) {
;           const int key = kt * 64 + s * 16 + fq * 4 + j;
;           if (key > qrow[qs]) x = -1e30f;
;         }
;         st[qs][s][j] = x;
;         tmax = fmaxf(tmax, x);
;       }
;     }
;     tmax = fmaxf(tmax, __shfl_xor(tmax, 16));
;     tmax = fmaxf(tmax, __shfl_xor(tmax, 32));
;     const float mn = fmaxf(m2[qs], tmax);
;     const float alpha = __builtin_amdgcn_exp2f(m2[qs] - mn);
;     m2[qs] = mn;
;     float ps = 0.f;
; #pragma unroll
;     for (int s = 0; s < 4; ++s)
; #pragma unroll
;       for (int j = 0; j < 4; ++j) {
;         const float pv = __builtin_amdgcn_exp2f(st[qs][s][j] - mn);
;         st[qs][s][j] = pv;
;         ps += pv;
;       }
;     l[qs] = l[qs] * alpha + ps;
; #pragma unroll
;     for (int n = 0; n < 4; ++n) { o[qs][n][0] *= alpha; o[qs][n][1] *= alpha; o[qs][n][2] *= alpha; o[qs][n][3] *= alpha; }
;     }
; #pragma unroll
;     for (int g = 0; g < 2; ++g) {
;       union { bf16x8 v; unsigned u[4]; } pk;
;       pk.u[0] = pack2bf(st[qs][2 * g][0], st[qs][2 * g][1]);
;       pk.u[1] = pack2bf(st[qs][2 * g][2], st[qs][2 * g][3]);
;       pk.u[2] = pack2bf(st[qs][2 * g + 1][0], st[qs][2 * g + 1][1]);
;       pk.u[3] = pack2bf(st[qs][2 * g + 1][2], st[qs][2 * g + 1][3]);
;       pf[qs][g] = pk.v;
;     }
; #pragma unroll
;     for (int n = 0; n < 4; ++n)
; #pragma unroll
	v_sub_f32_e32 v104, v157, v242
	v_cmp_gt_i32_e64 s[14:15], v214, v176
	v_cndmask_b32_e64 v112, v112, v202, s[12:13]
	v_cmp_gt_i32_e64 s[12:13], v221, v143
	v_fmac_f32_e32 v104, 0x3e38aa3b, v234
	s_and_b64 s[14:15], vcc, s[14:15]
	s_and_b64 s[12:13], vcc, s[12:13]
	v_cndmask_b32_e64 v104, v104, v202, s[14:15]
	v_cndmask_b32_e64 v114, v114, v202, s[12:13]
	v_cmp_gt_i32_e64 s[12:13], v220, v143
	v_exp_f32_e32 v135, v104
	v_sub_f32_e32 v104, v157, v243
	v_cmp_gt_i32_e64 s[14:15], v186, v176
	v_fmac_f32_e32 v120, 0x3e38aa3b, v126
	s_and_b64 s[12:13], vcc, s[12:13]
	v_fmac_f32_e32 v104, 0x3e38aa3b, v235
	s_and_b64 s[14:15], vcc, s[14:15]
	v_cndmask_b32_e64 v124, v120, v202, s[12:13]
	v_sub_f32_e32 v120, v177, v191
	v_cmp_gt_i32_e64 s[12:13], v219, v143
	v_cndmask_b32_e64 v104, v104, v202, s[14:15]
	v_fmac_f32_e32 v120, 0x3e38aa3b, v127
	s_and_b64 s[12:13], vcc, s[12:13]
	v_exp_f32_e32 v139, v104
	v_sub_f32_e32 v104, v157, v244
	v_cmp_gt_i32_e64 s[14:15], v184, v176
	v_cndmask_b32_e64 v125, v120, v202, s[12:13]
	v_sub_f32_e32 v120, v177, v238
	v_cmp_gt_i32_e64 s[12:13], v218, v143
	v_fmac_f32_e32 v104, 0x3e38aa3b, v236
	s_and_b64 s[14:15], vcc, s[14:15]
	v_fmac_f32_e32 v120, 0x3e38aa3b, v116
	s_and_b64 s[12:13], vcc, s[12:13]
	v_cndmask_b32_e64 v104, v104, v202, s[14:15]
	v_cndmask_b32_e64 v116, v120, v202, s[12:13]
	v_sub_f32_e32 v120, v177, v239
	v_cmp_gt_i32_e64 s[12:13], v217, v143
	v_exp_f32_e32 v183, v104
	v_sub_f32_e32 v104, v157, v245
	v_cmp_gt_i32_e64 s[14:15], v182, v176
	v_fmac_f32_e32 v120, 0x3e38aa3b, v117
	s_and_b64 s[12:13], vcc, s[12:13]
	v_fmac_f32_e32 v104, 0x3e38aa3b, v237
	s_and_b64 s[14:15], vcc, s[14:15]
	v_cndmask_b32_e64 v117, v120, v202, s[12:13]
	v_sub_f32_e32 v120, v177, v240
	v_cmp_gt_i32_e64 s[12:13], v216, v143
	v_cndmask_b32_e64 v104, v104, v202, s[14:15]
	v_cmp_gt_i32_e64 s[14:15], v222, v143
	v_fmac_f32_e32 v120, 0x3e38aa3b, v118
	s_and_b64 s[12:13], vcc, s[12:13]
	v_fmac_f32_e32 v228, 0x3e38aa3b, v230
	s_and_b64 s[14:15], vcc, s[14:15]
	v_cndmask_b32_e64 v118, v120, v202, s[12:13]
	v_sub_f32_e32 v120, v177, v241
	v_cmp_gt_i32_e64 s[12:13], v215, v143
	v_exp_f32_e32 v185, v104
	v_cndmask_b32_e64 v104, v228, v202, s[14:15]
	v_fmac_f32_e32 v227, 0x3e38aa3b, v231
	v_cmp_lt_i32_e64 s[14:15], v222, v143
	v_fmac_f32_e32 v120, 0x3e38aa3b, v119
	s_and_b64 s[12:13], vcc, s[12:13]
	v_cndmask_b32_e64 v106, v202, v227, s[14:15]
	v_cmp_gt_i32_e64 s[14:15], v224, v143
	v_cndmask_b32_e64 v119, v120, v202, s[12:13]
	v_sub_f32_e32 v120, v177, v242
	v_cmp_gt_i32_e64 s[12:13], v214, v143
	v_fmac_f32_e32 v226, 0x3e38aa3b, v232
	s_and_b64 s[14:15], vcc, s[14:15]
	v_fmac_f32_e32 v120, 0x3e38aa3b, v246
	s_and_b64 s[12:13], vcc, s[12:13]
	v_cndmask_b32_e64 v108, v226, v202, s[14:15]
	v_cmp_gt_i32_e64 s[14:15], v223, v143
	v_cndmask_b32_e64 v120, v120, v202, s[12:13]
	v_sub_f32_e32 v122, v177, v243
	v_cmp_gt_i32_e64 s[12:13], v186, v143
	v_fmac_f32_e32 v225, 0x3e38aa3b, v233
	s_and_b64 s[14:15], vcc, s[14:15]
	v_fmac_f32_e32 v122, 0x3e38aa3b, v247
	s_and_b64 s[12:13], vcc, s[12:13]
	v_cndmask_b32_e32 v106, v227, v106, vcc
	v_cndmask_b32_e64 v110, v225, v202, s[14:15]
	v_cndmask_b32_e64 v122, v122, v202, s[12:13]
	v_sub_f32_e32 v126, v177, v244
	v_cmp_gt_i32_e64 s[12:13], v184, v143
	v_exp_f32_e32 v137, v137
	v_fmac_f32_e32 v126, 0x3e38aa3b, v248
	s_and_b64 s[12:13], vcc, s[12:13]
	v_exp_f32_e32 v134, v120
	v_exp_f32_e32 v138, v122
	v_exp_f32_e32 v136, v104
	v_exp_f32_e32 v132, v106
	v_exp_f32_e32 v128, v108
	v_exp_f32_e32 v130, v110
	v_exp_f32_e32 v120, v112
	v_exp_f32_e32 v122, v114
	v_exp_f32_e32 v112, v124
	v_exp_f32_e32 v114, v125
	v_cndmask_b32_e64 v126, v126, v202, s[12:13]
	v_sub_f32_e32 v127, v177, v245
	v_cmp_gt_i32_e64 s[12:13], v182, v143
	v_fmac_f32_e32 v127, 0x3e38aa3b, v249
	s_and_b64 vcc, vcc, s[12:13]
	v_cndmask_b32_e32 v127, v127, v202, vcc
	v_cvt_pk_bf16_f32 v234, v137, v133
	v_cvt_pk_bf16_f32 v235, v129, v131
	v_cvt_pk_bf16_f32 v236, v121, v123
	v_cvt_pk_bf16_f32 v237, v113, v115
	v_exp_f32_e32 v182, v126
	v_exp_f32_e32 v104, v116
	v_exp_f32_e32 v106, v117
	v_exp_f32_e32 v108, v118
	v_exp_f32_e32 v110, v119
	v_exp_f32_e32 v184, v127
	v_cvt_pk_bf16_f32 v116, v136, v132
	v_cvt_pk_bf16_f32 v117, v128, v130
	v_cvt_pk_bf16_f32 v118, v120, v122
	v_cvt_pk_bf16_f32 v119, v112, v114
	v_mfma_f32_16x16x32_bf16 v[68:71], v[92:95], v[234:237], v[68:71]
	v_cvt_pk_bf16_f32 v250, v105, v107
	v_cvt_pk_bf16_f32 v251, v109, v111
	v_cvt_pk_bf16_f32 v252, v135, v139
	v_mfma_f32_16x16x32_bf16 v[64:67], v[92:95], v[116:119], v[64:67]
	v_cvt_pk_bf16_f32 v253, v183, v185
	v_cvt_pk_bf16_f32 v124, v104, v106
	v_cvt_pk_bf16_f32 v125, v108, v110
	v_cvt_pk_bf16_f32 v126, v134, v138
	v_cvt_pk_bf16_f32 v127, v182, v184
	v_mfma_f32_16x16x32_bf16 v[68:71], v[88:91], v[250:253], v[68:71]
	s_nop 0
	v_mfma_f32_16x16x32_bf16 v[64:67], v[88:91], v[124:127], v[64:67]
	v_add_f32_e64 v88, v136, 0
	v_add_f32_e64 v89, v137, 0
	v_pk_add_f32 v[88:89], v[88:89], v[132:133]
	v_mfma_f32_16x16x32_bf16 v[40:43], v[84:87], v[234:237], v[40:43]
	v_mfma_f32_16x16x32_bf16 v[8:11], v[84:87], v[116:119], v[8:11]
	v_add_f32_e64 v84, v128, v88
	v_add_f32_e64 v85, v129, v89
	v_pk_add_f32 v[84:85], v[130:131], v[84:85]
	v_mfma_f32_16x16x32_bf16 v[40:43], v[80:83], v[250:253], v[40:43]
	v_add_f32_e64 v84, v84, v120
	v_add_f32_e64 v85, v85, v121
	v_mfma_f32_16x16x32_bf16 v[8:11], v[80:83], v[124:127], v[8:11]
	v_add_f32_e64 v80, v122, v84
	v_add_f32_e64 v81, v123, v85
	v_pk_add_f32 v[80:81], v[112:113], v[80:81]
	v_mfma_f32_16x16x32_bf16 v[60:63], v[76:79], v[234:237], v[60:63]
	v_add_f32_e64 v80, v114, v80
	v_add_f32_e64 v81, v115, v81
	v_mfma_f32_16x16x32_bf16 v[4:7], v[76:79], v[116:119], v[4:7]
	v_add_f32_e64 v76, v104, v80
	v_add_f32_e64 v77, v105, v81
	v_pk_add_f32 v[76:77], v[106:107], v[76:77]
	v_mfma_f32_16x16x32_bf16 v[20:23], v[100:103], v[234:237], v[20:23]
	v_add_f32_e64 v76, v108, v76
	v_add_f32_e64 v77, v109, v77
	v_mfma_f32_16x16x32_bf16 v[0:3], v[100:103], v[116:119], v[0:3]
	v_mfma_f32_16x16x32_bf16 v[60:63], v[72:75], v[250:253], v[60:63]
	v_mfma_f32_16x16x32_bf16 v[4:7], v[72:75], v[124:127], v[4:7]
	v_add_f32_e64 v72, v110, v76
	v_add_f32_e64 v73, v111, v77
	v_pk_add_f32 v[72:73], v[134:135], v[72:73]
	v_mfma_f32_16x16x32_bf16 v[20:23], v[96:99], v[250:253], v[20:23]
	v_add_f32_e64 v72, v138, v72
	v_add_f32_e64 v73, v139, v73
	v_pk_add_f32 v[72:73], v[182:183], v[72:73]
	v_mfma_f32_16x16x32_bf16 v[0:3], v[96:99], v[124:127], v[0:3]
	v_add_f32_e64 v72, v184, v72
	v_add_f32_e64 v73, v185, v73
	v_pk_add_f32 v[178:179], v[178:179], v[72:73]

; template <bool BOUND>
; DEV void attn_tile(const char* kb_, const char* vb_, const float* cl, int kt, bool diag, const int (&qrow)[2], int fr, int fq,
;                    const float (&cq2)[2], const bf16x8 (&qf)[2][2], f32x4 (&o)[2][4], float (&m2)[2], float (&l)[2]) {
;     ...
; #pragma unroll
;   for (int s = 0; s < 4; ++s) {
;     const bf16x8 a0 = *(const bf16x8*)(kb_ + (s * 16 + fr) * 144 + fq * 16);
;     const bf16x8 a1 = *(const bf16x8*)(kb_ + (s * 16 + fr) * 144 + 64 + fq * 16);
; #pragma unroll
;     for (int qs = 0; qs < 2; ++qs) {
;       f32x4 z = f32x4{0.f, 0.f, 0.f, 0.f};
;       z = __builtin_amdgcn_mfma_f32_16x16x32_bf16(a0, qf[qs][0], z, 0, 0, 0);
;       st[qs][s] = __builtin_amdgcn_mfma_f32_16x16x32_bf16(a1, qf[qs][1], z, 0, 0, 0);
;     }
;   }
;   bf16x8 vf[4][2];
; #pragma unroll
;   for (int n = 0; n < 4; ++n)
; #pragma unroll
;     for (int g = 0; g < 2; ++g) {
;       const char* va = vb_ + (n * 16 + fr) * 144 + (g * 32 + fq * 4) * 2;
;       union { bf16x8 v; uint2 u[2]; } av;
;       av.u[0] = *(const uint2*)va;
;       av.u[1] = *(const uint2*)(va + 32);
;       vf[n][g] = av.v;
;     }
;   bf16x8 pf[2][2];
; #pragma unroll
;   for (int qs = 0; qs < 2; ++qs) {
;     if constexpr (BOUND) {
;       float ps = 0.f;
; #pragma unroll
;       for (int s = 0; s < 4; ++s) {
;         const float4 ck = *(const float4*)(cl + kt * 64 + s * 16 + fq * 4);
;         const float ckk[4] = {ck.x, ck.y, ck.z, ck.w};
; #pragma unroll
;         for (int j = 0; j < 4; ++j) {
;           float x = st[qs][s][j] * SC2 + (cq2[qs] - ckk[j]);
;           if (diag) {
;             const int key = kt * 64 + s * 16 + fq * 4 + j;
;             if (key > qrow[qs]) x = -1e30f;
;           }
;           const float pv = __builtin_amdgcn_exp2f(x);
;           st[qs][s][j] = pv;
;           ps += pv;
;         }
;       }
;       l[qs] += ps;
.Lattn_nm0:
	v_mfma_f32_16x16x32_bf16 v[230:233], v[132:135], v[12:15], 0
	ds_read_b128 v[242:245], v140 offset:36992
	v_mfma_f32_16x16x32_bf16 v[230:233], v[128:131], v[16:19], v[230:233]
	v_mfma_f32_16x16x32_bf16 v[234:237], v[132:135], v[28:31], 0
	v_mfma_f32_16x16x32_bf16 v[238:241], v[124:127], v[12:15], 0
	s_nop 5
	v_fmac_f32_e32 v139, 0x3e38aa3b, v231
	v_fmac_f32_e32 v137, 0x3e38aa3b, v230
	v_fmac_f32_e32 v138, 0x3e38aa3b, v232
	v_fmac_f32_e32 v136, 0x3e38aa3b, v233
	ds_read_b128 v[230:233], v140 offset:36928
	v_mfma_f32_16x16x32_bf16 v[234:237], v[128:131], v[24:27], v[234:237]
	v_mov_b32_e32 v128, v138
	v_mfma_f32_16x16x32_bf16 v[238:241], v[120:123], v[16:19], v[238:241]
	v_exp_f32_e32 v129, v128
	v_mov_b32_e32 v128, v136
	v_exp_f32_e32 v131, v128
	v_mfma_f32_16x16x32_bf16 v[124:127], v[124:127], v[28:31], 0
	s_waitcnt lgkmcnt(0)
	v_sub_f32_e32 v128, v157, v230
	s_nop 0
	s_nop 0
	v_fmac_f32_e32 v128, 0x3e38aa3b, v238
	v_mfma_f32_16x16x32_bf16 v[124:127], v[120:123], v[24:27], v[124:127]
	v_mov_b32_e32 v120, v128
	v_exp_f32_e32 v121, v120
	v_sub_f32_e32 v120, v157, v231
	v_mfma_f32_16x16x32_bf16 v[246:249], v[116:119], v[12:15], 0
	v_fmac_f32_e32 v120, 0x3e38aa3b, v239
	v_mfma_f32_16x16x32_bf16 v[116:119], v[116:119], v[28:31], 0
	v_exp_f32_e32 v123, v120
	v_sub_f32_e32 v120, v157, v232
	v_fmac_f32_e32 v120, 0x3e38aa3b, v240
	v_mfma_f32_16x16x32_bf16 v[246:249], v[112:115], v[16:19], v[246:249]
	v_exp_f32_e32 v133, v139
	v_mfma_f32_16x16x32_bf16 v[116:119], v[112:115], v[24:27], v[116:119]
	v_mov_b32_e32 v112, v120
	v_exp_f32_e32 v113, v112
	v_sub_f32_e32 v112, v157, v233
	v_mfma_f32_16x16x32_bf16 v[250:253], v[108:111], v[12:15], 0
	v_fmac_f32_e32 v112, 0x3e38aa3b, v241
	v_mfma_f32_16x16x32_bf16 v[108:111], v[108:111], v[28:31], 0
	v_exp_f32_e32 v115, v112
	v_sub_f32_e32 v112, v157, v242
	v_fmac_f32_e32 v112, 0x3e38aa3b, v246
	s_nop 0
	v_mfma_f32_16x16x32_bf16 v[238:241], v[104:107], v[16:19], v[250:253]
	v_sub_f32_e32 v114, v177, v231
	v_fmac_f32_e32 v114, 0x3e38aa3b, v125
	v_sub_f32_e32 v120, v177, v232
	v_mfma_f32_16x16x32_bf16 v[250:253], v[104:107], v[24:27], v[108:111]
	v_mov_b32_e32 v104, v112
	v_exp_f32_e32 v105, v104
	v_sub_f32_e32 v104, v157, v243
	v_fmac_f32_e32 v104, 0x3e38aa3b, v247
	v_exp_f32_e32 v107, v104
	v_sub_f32_e32 v104, v157, v244
	v_fmac_f32_e32 v104, 0x3e38aa3b, v248
	v_exp_f32_e32 v109, v104
	v_sub_f32_e32 v104, v157, v245
	v_fmac_f32_e32 v104, 0x3e38aa3b, v249
	ds_read_b128 v[246:249], v140 offset:37056
	v_sub_f32_e32 v112, v177, v230
	v_fmac_f32_e32 v112, 0x3e38aa3b, v124
	v_exp_f32_e32 v111, v104
	s_waitcnt lgkmcnt(0)
	v_sub_f32_e32 v104, v157, v246
	v_fmac_f32_e32 v104, 0x3e38aa3b, v238
	v_exp_f32_e32 v135, v104
	v_sub_f32_e32 v104, v157, v247
	v_fmac_f32_e32 v120, 0x3e38aa3b, v126
	v_fmac_f32_e32 v104, 0x3e38aa3b, v239
	v_mov_b32_e32 v124, v120
	v_sub_f32_e32 v120, v177, v233
	v_fmac_f32_e32 v120, 0x3e38aa3b, v127
	v_exp_f32_e32 v139, v104
	v_sub_f32_e32 v104, v157, v248
	v_mov_b32_e32 v125, v120
	v_sub_f32_e32 v120, v177, v242
	v_fmac_f32_e32 v104, 0x3e38aa3b, v240
	v_fmac_f32_e32 v120, 0x3e38aa3b, v116
	v_mov_b32_e32 v116, v120
	v_sub_f32_e32 v120, v177, v243
	v_exp_f32_e32 v183, v104
	v_sub_f32_e32 v104, v157, v249
	v_fmac_f32_e32 v120, 0x3e38aa3b, v117
	v_fmac_f32_e32 v104, 0x3e38aa3b, v241
	v_mov_b32_e32 v117, v120
	v_sub_f32_e32 v120, v177, v244
	v_fmac_f32_e32 v120, 0x3e38aa3b, v118
	v_fmac_f32_e32 v228, 0x3e38aa3b, v234
	v_mov_b32_e32 v118, v120
	v_sub_f32_e32 v120, v177, v245
	v_exp_f32_e32 v185, v104
	v_mov_b32_e32 v104, v228
	v_fmac_f32_e32 v227, 0x3e38aa3b, v235
	v_fmac_f32_e32 v120, 0x3e38aa3b, v119
	v_mov_b32_e32 v119, v120
	v_sub_f32_e32 v120, v177, v246
	v_fmac_f32_e32 v226, 0x3e38aa3b, v236
	v_fmac_f32_e32 v120, 0x3e38aa3b, v250
	v_mov_b32_e32 v108, v226
	v_sub_f32_e32 v122, v177, v247
	v_fmac_f32_e32 v225, 0x3e38aa3b, v237
	v_fmac_f32_e32 v122, 0x3e38aa3b, v251
	v_mov_b32_e32 v106, v227
	v_mov_b32_e32 v110, v225
	v_sub_f32_e32 v126, v177, v248
	v_exp_f32_e32 v137, v137
	v_fmac_f32_e32 v126, 0x3e38aa3b, v252
	v_exp_f32_e32 v134, v120
	v_exp_f32_e32 v138, v122
	v_exp_f32_e32 v136, v104
	v_exp_f32_e32 v132, v106
	v_exp_f32_e32 v128, v108
	v_exp_f32_e32 v130, v110
	v_exp_f32_e32 v120, v112
	v_exp_f32_e32 v122, v114
	v_exp_f32_e32 v112, v124
	v_exp_f32_e32 v114, v125
	v_sub_f32_e32 v127, v177, v249
	v_fmac_f32_e32 v127, 0x3e38aa3b, v253
	v_cvt_pk_bf16_f32 v238, v137, v133
	v_cvt_pk_bf16_f32 v239, v129, v131
	v_cvt_pk_bf16_f32 v240, v121, v123
	v_cvt_pk_bf16_f32 v241, v113, v115
	v_exp_f32_e32 v182, v126
	v_exp_f32_e32 v104, v116
	v_exp_f32_e32 v106, v117
	v_exp_f32_e32 v108, v118
	v_exp_f32_e32 v110, v119
	v_exp_f32_e32 v184, v127
	v_cvt_pk_bf16_f32 v116, v136, v132
	v_cvt_pk_bf16_f32 v117, v128, v130
	v_cvt_pk_bf16_f32 v118, v120, v122
	v_cvt_pk_bf16_f32 v119, v112, v114
	v_mfma_f32_16x16x32_bf16 v[68:71], v[92:95], v[238:241], v[68:71]
	v_cvt_pk_bf16_f32 v188, v105, v107
	v_cvt_pk_bf16_f32 v189, v109, v111
	v_cvt_pk_bf16_f32 v190, v135, v139
	v_mfma_f32_16x16x32_bf16 v[64:67], v[92:95], v[116:119], v[64:67]
	v_cvt_pk_bf16_f32 v191, v183, v185
	v_cvt_pk_bf16_f32 v124, v104, v106
	v_cvt_pk_bf16_f32 v125, v108, v110
	v_cvt_pk_bf16_f32 v126, v134, v138
	v_cvt_pk_bf16_f32 v127, v182, v184
	v_mfma_f32_16x16x32_bf16 v[68:71], v[88:91], v[188:191], v[68:71]
	s_nop 0
	v_mfma_f32_16x16x32_bf16 v[64:67], v[88:91], v[124:127], v[64:67]
	v_add_f32_e64 v88, v136, 0
	v_add_f32_e64 v89, v137, 0
	v_pk_add_f32 v[88:89], v[88:89], v[132:133]
	v_mfma_f32_16x16x32_bf16 v[40:43], v[84:87], v[238:241], v[40:43]
	v_mfma_f32_16x16x32_bf16 v[8:11], v[84:87], v[116:119], v[8:11]
	v_add_f32_e64 v84, v128, v88
; template <bool BOUND>
; DEV void attn_tile(const char* kb_, const char* vb_, const float* cl, int kt, bool diag, const int (&qrow)[2], int fr, int fq,
;                    const float (&cq2)[2], const bf16x8 (&qf)[2][2], f32x4 (&o)[2][4], float (&m2)[2], float (&l)[2]) {
;     ...
; #pragma unroll
;   for (int s = 0; s < 4; ++s) {
;     const bf16x8 a0 = *(const bf16x8*)(kb_ + (s * 16 + fr) * 144 + fq * 16);
;     const bf16x8 a1 = *(const bf16x8*)(kb_ + (s * 16 + fr) * 144 + 64 + fq * 16);
; #pragma unroll
;     for (int qs = 0; qs < 2; ++qs) {
;       f32x4 z = f32x4{0.f, 0.f, 0.f, 0.f};
;       z = __builtin_amdgcn_mfma_f32_16x16x32_bf16(a0, qf[qs][0], z, 0, 0, 0);
;       st[qs][s] = __builtin_amdgcn_mfma_f32_16x16x32_bf16(a1, qf[qs][1], z, 0, 0, 0);
;     }
;   }
;   bf16x8 vf[4][2];
; #pragma unroll
;   for (int n = 0; n < 4; ++n)
; #pragma unroll
;     for (int g = 0; g < 2; ++g) {
;       const char* va = vb_ + (n * 16 + fr) * 144 + (g * 32 + fq * 4) * 2;
;       union { bf16x8 v; uint2 u[2]; } av;
;       av.u[0] = *(const uint2*)va;
;       av.u[1] = *(const uint2*)(va + 32);
;       vf[n][g] = av.v;
;     }
;   bf16x8 pf[2][2];
; #pragma unroll
;   for (int qs = 0; qs < 2; ++qs) {
;     if constexpr (BOUND) {
;       float ps = 0.f;
; #pragma unroll
;       for (int s = 0; s < 4; ++s) {
;         const float4 ck = *(const float4*)(cl + kt * 64 + s * 16 + fq * 4);
;         const float ckk[4] = {ck.x, ck.y, ck.z, ck.w};
; #pragma unroll
;         for (int j = 0; j < 4; ++j) {
;           float x = st[qs][s][j] * SC2 + (cq2[qs] - ckk[j]);
;           if (diag) {
;             const int key = kt * 64 + s * 16 + fq * 4 + j;
;             if (key > qrow[qs]) x = -1e30f;
;           }
;           const float pv = __builtin_amdgcn_exp2f(x);
;     ...
; #pragma unroll
;     for (int g = 0; g < 2; ++g) {
;       union { bf16x8 v; unsigned u[4]; } pk;
;       pk.u[0] = pack2bf(st[qs][2 * g][0], st[qs][2 * g][1]);
;       pk.u[1] = pack2bf(st[qs][2 * g][2], st[qs][2 * g][3]);
;       pk.u[2] = pack2bf(st[qs][2 * g + 1][0], st[qs][2 * g + 1][1]);
;       pk.u[3] = pack2bf(st[qs][2 * g + 1][2], st[qs][2 * g + 1][3]);
;       pf[qs][g] = pk.v;
;     }
; #pragma unroll
;     for (int n = 0; n < 4; ++n)
; #pragma unroll
;       for (int g = 0; g < 2; ++g) o[qs][n] = __builtin_amdgcn_mfma_f32_16x16x32_bf16(vf[n][g], pf[qs][g], o[qs][n], 0, 0, 0);
	v_add_f32_e64 v85, v129, v89
	v_pk_add_f32 v[84:85], v[130:131], v[84:85]
	v_mfma_f32_16x16x32_bf16 v[40:43], v[80:83], v[188:191], v[40:43]
	v_add_f32_e64 v84, v84, v120
	v_add_f32_e64 v85, v85, v121
	v_mfma_f32_16x16x32_bf16 v[8:11], v[80:83], v[124:127], v[8:11]
	v_add_f32_e64 v80, v122, v84
	v_add_f32_e64 v81, v123, v85
	v_pk_add_f32 v[80:81], v[112:113], v[80:81]
	v_mfma_f32_16x16x32_bf16 v[60:63], v[76:79], v[238:241], v[60:63]
	v_add_f32_e64 v80, v114, v80
	v_add_f32_e64 v81, v115, v81
	v_mfma_f32_16x16x32_bf16 v[4:7], v[76:79], v[116:119], v[4:7]
	v_add_f32_e64 v76, v104, v80
	v_add_f32_e64 v77, v105, v81
	v_pk_add_f32 v[76:77], v[106:107], v[76:77]
	v_mfma_f32_16x16x32_bf16 v[20:23], v[100:103], v[238:241], v[20:23]
	v_add_f32_e64 v76, v108, v76
	v_add_f32_e64 v77, v109, v77
	v_mfma_f32_16x16x32_bf16 v[0:3], v[100:103], v[116:119], v[0:3]
	v_mfma_f32_16x16x32_bf16 v[60:63], v[72:75], v[188:191], v[60:63]
	v_mfma_f32_16x16x32_bf16 v[4:7], v[72:75], v[124:127], v[4:7]
	v_add_f32_e64 v72, v110, v76
	v_add_f32_e64 v73, v111, v77
	v_pk_add_f32 v[72:73], v[134:135], v[72:73]
	v_mfma_f32_16x16x32_bf16 v[20:23], v[96:99], v[188:191], v[20:23]
	v_add_f32_e64 v72, v138, v72
	v_add_f32_e64 v73, v139, v73
	v_pk_add_f32 v[72:73], v[182:183], v[72:73]
	v_mfma_f32_16x16x32_bf16 v[0:3], v[96:99], v[124:127], v[0:3]
	v_add_f32_e64 v72, v184, v72
	v_add_f32_e64 v73, v185, v73
	v_pk_add_f32 v[178:179], v[178:179], v[72:73]
	s_branch .LBB0_824
.Lattn_nm1:
	v_mfma_f32_16x16x32_bf16 v[188:191], v[132:135], v[12:15], 0
	ds_read_b128 v[238:241], v140 offset:36992
	v_mfma_f32_16x16x32_bf16 v[188:191], v[128:131], v[16:19], v[188:191]
	v_mfma_f32_16x16x32_bf16 v[230:233], v[132:135], v[28:31], 0
	v_mfma_f32_16x16x32_bf16 v[234:237], v[124:127], v[12:15], 0
	s_nop 5
	v_fmac_f32_e32 v139, 0x3e38aa3b, v189
	v_fmac_f32_e32 v137, 0x3e38aa3b, v188
	v_fmac_f32_e32 v138, 0x3e38aa3b, v190
	v_fmac_f32_e32 v136, 0x3e38aa3b, v191
	ds_read_b128 v[188:191], v140 offset:36928
	v_mfma_f32_16x16x32_bf16 v[230:233], v[128:131], v[24:27], v[230:233]
	v_mov_b32_e32 v128, v138
	v_mfma_f32_16x16x32_bf16 v[234:237], v[120:123], v[16:19], v[234:237]
	v_exp_f32_e32 v129, v128
	v_mov_b32_e32 v128, v136
	v_exp_f32_e32 v131, v128
	v_mfma_f32_16x16x32_bf16 v[124:127], v[124:127], v[28:31], 0
	s_waitcnt lgkmcnt(0)
	v_sub_f32_e32 v128, v157, v188
	s_nop 0
	s_nop 0
	v_fmac_f32_e32 v128, 0x3e38aa3b, v234
	v_mfma_f32_16x16x32_bf16 v[124:127], v[120:123], v[24:27], v[124:127]
	v_mov_b32_e32 v120, v128
	v_exp_f32_e32 v121, v120
	v_sub_f32_e32 v120, v157, v189
	v_mfma_f32_16x16x32_bf16 v[242:245], v[116:119], v[12:15], 0
	v_fmac_f32_e32 v120, 0x3e38aa3b, v235
	v_mfma_f32_16x16x32_bf16 v[116:119], v[116:119], v[28:31], 0
	v_exp_f32_e32 v123, v120
	v_sub_f32_e32 v120, v157, v190
	v_fmac_f32_e32 v120, 0x3e38aa3b, v236
	v_mfma_f32_16x16x32_bf16 v[242:245], v[112:115], v[16:19], v[242:245]
	v_exp_f32_e32 v133, v139
	v_mfma_f32_16x16x32_bf16 v[116:119], v[112:115], v[24:27], v[116:119]
	v_mov_b32_e32 v112, v120
	v_exp_f32_e32 v113, v112
	v_sub_f32_e32 v112, v157, v191
	v_mfma_f32_16x16x32_bf16 v[246:249], v[108:111], v[12:15], 0
	v_fmac_f32_e32 v112, 0x3e38aa3b, v237
	v_mfma_f32_16x16x32_bf16 v[108:111], v[108:111], v[28:31], 0
	v_exp_f32_e32 v115, v112
	v_sub_f32_e32 v112, v157, v238
	v_fmac_f32_e32 v112, 0x3e38aa3b, v242
	s_nop 0
	v_mfma_f32_16x16x32_bf16 v[234:237], v[104:107], v[16:19], v[246:249]
	v_sub_f32_e32 v114, v177, v189
	v_fmac_f32_e32 v114, 0x3e38aa3b, v125
	v_sub_f32_e32 v120, v177, v190
	v_mfma_f32_16x16x32_bf16 v[246:249], v[104:107], v[24:27], v[108:111]
	v_mov_b32_e32 v104, v112
	v_exp_f32_e32 v105, v104
	v_sub_f32_e32 v104, v157, v239
	v_fmac_f32_e32 v104, 0x3e38aa3b, v243
	v_exp_f32_e32 v107, v104
	v_sub_f32_e32 v104, v157, v240
	v_fmac_f32_e32 v104, 0x3e38aa3b, v244
	v_exp_f32_e32 v109, v104
	v_sub_f32_e32 v104, v157, v241
	v_fmac_f32_e32 v104, 0x3e38aa3b, v245
	ds_read_b128 v[242:245], v140 offset:37056
	v_sub_f32_e32 v112, v177, v188
	v_fmac_f32_e32 v112, 0x3e38aa3b, v124
	v_exp_f32_e32 v111, v104
	s_waitcnt lgkmcnt(0)
; template <bool BOUND>
; DEV void attn_tile(const char* kb_, const char* vb_, const float* cl, int kt, bool diag, const int (&qrow)[2], int fr, int fq,
;                    const float (&cq2)[2], const bf16x8 (&qf)[2][2], f32x4 (&o)[2][4], float (&m2)[2], float (&l)[2]) {
;     ...
;         for (int j = 0; j < 4; ++j) {
;           float x = st[qs][s][j] * SC2 + (cq2[qs] - ckk[j]);
;           if (diag) {
;             const int key = kt * 64 + s * 16 + fq * 4 + j;
;             if (key > qrow[qs]) x = -1e30f;
;           }
;           const float pv = __builtin_amdgcn_exp2f(x);
;           st[qs][s][j] = pv;
;           ps += pv;
;         }
;       }
;       l[qs] += ps;
;     } else {
;     float tmax = -1e30f;
; #pragma unroll
;     for (int s = 0; s < 4; ++s) {
;       const float4 ck = *(const float4*)(cl + kt * 64 + s * 16 + fq * 4);
;       const float ckk[4] = {ck.x, ck.y, ck.z, ck.w};
; #pragma unroll
;       for (int j = 0; j < 4; ++j) {
;         float x = st[qs][s][j] * SC2 + (cq2[qs] - ckk[j]);
;         if (diag) {
;           const int key = kt * 64 + s * 16 + fq * 4 + j;
;           if (key > qrow[qs]) x = -1e30f;
;         }
;         st[qs][s][j] = x;
;         tmax = fmaxf(tmax, x);
;       }
;     }
;     tmax = fmaxf(tmax, __shfl_xor(tmax, 16));
;     tmax = fmaxf(tmax, __shfl_xor(tmax, 32));
;     const float mn = fmaxf(m2[qs], tmax);
;     const float alpha = __builtin_amdgcn_exp2f(m2[qs] - mn);
;     m2[qs] = mn;
;     float ps = 0.f;
; #pragma unroll
;     for (int s = 0; s < 4; ++s)
; #pragma unroll
;       for (int j = 0; j < 4; ++j) {
;         const float pv = __builtin_amdgcn_exp2f(st[qs][s][j] - mn);
;         st[qs][s][j] = pv;
;         ps += pv;
;       }
;     l[qs] = l[qs] * alpha + ps;
; #pragma unroll
;     for (int n = 0; n < 4; ++n) { o[qs][n][0] *= alpha; o[qs][n][1] *= alpha; o[qs][n][2] *= alpha; o[qs][n][3] *= alpha; }
;     }
; #pragma unroll
;     for (int g = 0; g < 2; ++g) {
;       union { bf16x8 v; unsigned u[4]; } pk;
;       pk.u[0] = pack2bf(st[qs][2 * g][0], st[qs][2 * g][1]);
;       pk.u[1] = pack2bf(st[qs][2 * g][2], st[qs][2 * g][3]);
;       pk.u[2] = pack2bf(st[qs][2 * g + 1][0], st[qs][2 * g + 1][1]);
;       pk.u[3] = pack2bf(st[qs][2 * g + 1][2], st[qs][2 * g + 1][3]);
;       pf[qs][g] = pk.v;
;     }
; #pragma unroll
;     for (int n = 0; n < 4; ++n)
; #pragma unroll
	v_sub_f32_e32 v104, v157, v242
	v_fmac_f32_e32 v104, 0x3e38aa3b, v234
	v_exp_f32_e32 v135, v104
	v_sub_f32_e32 v104, v157, v243
	v_fmac_f32_e32 v120, 0x3e38aa3b, v126
	v_fmac_f32_e32 v104, 0x3e38aa3b, v235
	v_mov_b32_e32 v124, v120
	v_sub_f32_e32 v120, v177, v191
	v_fmac_f32_e32 v120, 0x3e38aa3b, v127
	v_exp_f32_e32 v139, v104
	v_sub_f32_e32 v104, v157, v244
	v_mov_b32_e32 v125, v120
	v_sub_f32_e32 v120, v177, v238
	v_fmac_f32_e32 v104, 0x3e38aa3b, v236
	v_fmac_f32_e32 v120, 0x3e38aa3b, v116
	v_mov_b32_e32 v116, v120
	v_sub_f32_e32 v120, v177, v239
	v_exp_f32_e32 v183, v104
	v_sub_f32_e32 v104, v157, v245
	v_fmac_f32_e32 v120, 0x3e38aa3b, v117
	v_fmac_f32_e32 v104, 0x3e38aa3b, v237
	v_mov_b32_e32 v117, v120
	v_sub_f32_e32 v120, v177, v240
	v_fmac_f32_e32 v120, 0x3e38aa3b, v118
	v_fmac_f32_e32 v228, 0x3e38aa3b, v230
	v_mov_b32_e32 v118, v120
	v_sub_f32_e32 v120, v177, v241
	v_exp_f32_e32 v185, v104
	v_mov_b32_e32 v104, v228
	v_fmac_f32_e32 v227, 0x3e38aa3b, v231
	v_fmac_f32_e32 v120, 0x3e38aa3b, v119
	v_mov_b32_e32 v119, v120
	v_sub_f32_e32 v120, v177, v242
	v_fmac_f32_e32 v226, 0x3e38aa3b, v232
	v_fmac_f32_e32 v120, 0x3e38aa3b, v246
	v_mov_b32_e32 v108, v226
	v_sub_f32_e32 v122, v177, v243
	v_fmac_f32_e32 v225, 0x3e38aa3b, v233
	v_fmac_f32_e32 v122, 0x3e38aa3b, v247
	v_mov_b32_e32 v106, v227
	v_mov_b32_e32 v110, v225
	v_sub_f32_e32 v126, v177, v244
	v_exp_f32_e32 v137, v137
	v_fmac_f32_e32 v126, 0x3e38aa3b, v248
	v_exp_f32_e32 v134, v120
	v_exp_f32_e32 v138, v122
	v_exp_f32_e32 v136, v104
	v_exp_f32_e32 v132, v106
	v_exp_f32_e32 v128, v108
	v_exp_f32_e32 v130, v110
	v_exp_f32_e32 v120, v112
	v_exp_f32_e32 v122, v114
	v_exp_f32_e32 v112, v124
	v_exp_f32_e32 v114, v125
	v_sub_f32_e32 v127, v177, v245
	v_fmac_f32_e32 v127, 0x3e38aa3b, v249
	v_cvt_pk_bf16_f32 v234, v137, v133
	v_cvt_pk_bf16_f32 v235, v129, v131
	v_cvt_pk_bf16_f32 v236, v121, v123
	v_cvt_pk_bf16_f32 v237, v113, v115
	v_exp_f32_e32 v182, v126
	v_exp_f32_e32 v104, v116
	v_exp_f32_e32 v106, v117
	v_exp_f32_e32 v108, v118
	v_exp_f32_e32 v110, v119
	v_exp_f32_e32 v184, v127
	v_cvt_pk_bf16_f32 v116, v136, v132
	v_cvt_pk_bf16_f32 v117, v128, v130
	v_cvt_pk_bf16_f32 v118, v120, v122
	v_cvt_pk_bf16_f32 v119, v112, v114
	v_mfma_f32_16x16x32_bf16 v[68:71], v[92:95], v[234:237], v[68:71]
	v_cvt_pk_bf16_f32 v250, v105, v107
	v_cvt_pk_bf16_f32 v251, v109, v111
	v_cvt_pk_bf16_f32 v252, v135, v139
	v_mfma_f32_16x16x32_bf16 v[64:67], v[92:95], v[116:119], v[64:67]
	v_cvt_pk_bf16_f32 v253, v183, v185
	v_cvt_pk_bf16_f32 v124, v104, v106
	v_cvt_pk_bf16_f32 v125, v108, v110
	v_cvt_pk_bf16_f32 v126, v134, v138
	v_cvt_pk_bf16_f32 v127, v182, v184
	v_mfma_f32_16x16x32_bf16 v[68:71], v[88:91], v[250:253], v[68:71]
	s_nop 0
	v_mfma_f32_16x16x32_bf16 v[64:67], v[88:91], v[124:127], v[64:67]
	v_add_f32_e64 v88, v136, 0
	v_add_f32_e64 v89, v137, 0
	v_pk_add_f32 v[88:89], v[88:89], v[132:133]
	v_mfma_f32_16x16x32_bf16 v[40:43], v[84:87], v[234:237], v[40:43]
	v_mfma_f32_16x16x32_bf16 v[8:11], v[84:87], v[116:119], v[8:11]
	v_add_f32_e64 v84, v128, v88
	v_add_f32_e64 v85, v129, v89
	v_pk_add_f32 v[84:85], v[130:131], v[84:85]
	v_mfma_f32_16x16x32_bf16 v[40:43], v[80:83], v[250:253], v[40:43]
	v_add_f32_e64 v84, v84, v120
	v_add_f32_e64 v85, v85, v121
	v_mfma_f32_16x16x32_bf16 v[8:11], v[80:83], v[124:127], v[8:11]
	v_add_f32_e64 v80, v122, v84
	v_add_f32_e64 v81, v123, v85
	v_pk_add_f32 v[80:81], v[112:113], v[80:81]
	v_mfma_f32_16x16x32_bf16 v[60:63], v[76:79], v[234:237], v[60:63]
	v_add_f32_e64 v80, v114, v80
	v_add_f32_e64 v81, v115, v81
	v_mfma_f32_16x16x32_bf16 v[4:7], v[76:79], v[116:119], v[4:7]
	v_add_f32_e64 v76, v104, v80
	v_add_f32_e64 v77, v105, v81
	v_pk_add_f32 v[76:77], v[106:107], v[76:77]
	v_mfma_f32_16x16x32_bf16 v[20:23], v[100:103], v[234:237], v[20:23]
	v_add_f32_e64 v76, v108, v76
	v_add_f32_e64 v77, v109, v77
	v_mfma_f32_16x16x32_bf16 v[0:3], v[100:103], v[116:119], v[0:3]
	v_mfma_f32_16x16x32_bf16 v[60:63], v[72:75], v[250:253], v[60:63]
	v_mfma_f32_16x16x32_bf16 v[4:7], v[72:75], v[124:127], v[4:7]
	v_add_f32_e64 v72, v110, v76
	v_add_f32_e64 v73, v111, v77
	v_pk_add_f32 v[72:73], v[134:135], v[72:73]
	v_mfma_f32_16x16x32_bf16 v[20:23], v[96:99], v[250:253], v[20:23]
	v_add_f32_e64 v72, v138, v72
	v_add_f32_e64 v73, v139, v73
	v_pk_add_f32 v[72:73], v[182:183], v[72:73]
	v_mfma_f32_16x16x32_bf16 v[0:3], v[96:99], v[124:127], v[0:3]
	v_add_f32_e64 v72, v184, v72
	v_add_f32_e64 v73, v185, v73
	v_pk_add_f32 v[178:179], v[178:179], v[72:73]
	s_branch .LBB0_846
